# hyena unit start: touch the channel's tap array and its z / x0 rows once (loads into unused registers) so the later staging rounds hit cache, on top of v33
# baseline (speedup 1.0000x reference)
.LBB0_473:
	s_ashr_i32 s3, s2, 31
	s_lshl_b64 s[0:1], s[2:3], 2
	v_readlane_b32 s4, v254, 28
	v_readlane_b32 s5, v254, 29
	s_add_u32 s4, s4, s0
	s_addc_u32 s5, s5, s1
	v_mov_b32_e32 v77, v198
	s_nop 1
	global_load_dword v75, v1, s[4:5]
	v_readlane_b32 s4, v254, 37
	v_readlane_b32 s5, v254, 38
	s_add_u32 s0, s4, s0
	s_addc_u32 s1, s5, s1
	global_load_dword v74, v1, s[0:1]
	s_movk_i32 s0, 0x804
	s_nop 0
	v_readfirstlane_b32 s10, v77
	v_cmp_gt_i32_e32 vcc, s0, v77
	v_lshlrev_b32_e32 v76, 3, v77
	s_and_saveexec_b64 s[4:5], vcc
	s_cbranch_execz .LBB0_494
	s_lshl_b64 s[0:1], s[2:3], 16
	v_readlane_b32 s6, v254, 30
	v_lshlrev_b32_e32 v3, 5, v77
	s_add_u32 s6, s6, s0
	v_readlane_b32 s0, v254, 31
	v_sub_u32_e32 v3, 0, v3
	s_addc_u32 s7, s0, s1
	v_add_u32_e32 v2, 0xfffffe00, v77
	v_lshlrev_b32_e32 v0, 3, v77
	v_add_u32_e32 v3, 0x10070, v3
	v_lshlrev_b32_e32 v88, 4, v77
	global_load_dwordx4 v[82:85], v88, s[6:7]
	v_add_u32_e32 v86, 0x2000, v88
	global_load_dwordx4 v[82:85], v86, s[6:7]
	v_add_u32_e32 v87, 0x4000, v88
	global_load_dwordx4 v[82:85], v87, s[6:7]
	v_add_u32_e32 v86, 0x6000, v88
	global_load_dwordx4 v[82:85], v86, s[6:7]
	v_add_u32_e32 v87, 0x8000, v88
	global_load_dwordx4 v[82:85], v87, s[6:7]
	v_add_u32_e32 v86, 0xa000, v88
	global_load_dwordx4 v[82:85], v86, s[6:7]
	v_add_u32_e32 v87, 0xc000, v88
	global_load_dwordx4 v[82:85], v87, s[6:7]
	v_add_u32_e32 v86, 0xe000, v88
	global_load_dwordx4 v[82:85], v86, s[6:7]
	s_mul_i32 s36, s2, 0x4200
	s_add_u32 s38, s18, s36
	s_addc_u32 s39, s19, 0
	v_readlane_b32 s40, v251, 35
	v_readlane_b32 s41, v251, 36
	v_lshlrev_b32_e32 v89, 5, v77
	v_add_u32_e32 v90, 0x420000, v89
	global_load_dwordx4 v[82:85], v89, s[38:39] offset:512
	global_load_dwordx4 v[82:85], v89, s[38:39] offset:528
	global_load_dwordx4 v[82:85], v90, s[38:39] offset:512
	global_load_dwordx4 v[82:85], v90, s[38:39] offset:528
	s_add_u32 s40, s40, s36
	s_addc_u32 s41, s41, 0
	global_load_dwordx4 v[82:85], v89, s[40:41] offset:512
	global_load_dwordx4 v[82:85], v89, s[40:41] offset:528
	global_load_dwordx4 v[82:85], v90, s[40:41] offset:512
	global_load_dwordx4 v[82:85], v90, s[40:41] offset:528
	s_mov_b64 s[8:9], 0
	s_branch .LBB0_476
